# scan / up-projection phase staggered three ways by XCD (scan first; q-GEMM, scan, kv-GEMM; both GEMMs first)
# baseline (speedup 1.0000x reference)
;     __host__ __device__ void init(int N, int K, int G_, int c_, int mode_, int rev_ = 0) { so.init(128 * BM, N, K, G_, c_, rev_); nN = N / BM; mode = mode_; }
; #define LAUNDER() int tid = tid0; asm volatile("" : "+v"(tid)); int wg = blockIdx.x; asm volatile("" : "+s"(wg)); const int lane = tid & 63, wave = __builtin_amdgcn_readfirstlane(tid >> 6), gw = wg * NWAVES + wave, NGW = G * NWAVES; (void)lane; (void)wave; (void)gw; (void)NGW
; __global__ void __launch_bounds__(NTHR, 2) fwd_kernel(Args a) {
;     ...
;         { LAUNDER(); mlstm_scan(DC, DN, SC, wg, G, tid); }
;         __syncthreads();
;         { LAUNDER(); pg8::Gemm g{Z + ZQ, WUQ, MTOK, 768, 512}; pg8::StaticOrder S; S.init(MTOK, 768, 512, G, wg, 1);
;           pg8::EpiBf16<0, false, true, 512, false> E{QM, 768, nullptr, rs2, nullptr, 0};
;           pg8::gemm_phase<pg8::EpiBf16<0, false, true, 512, false>, pg8::StaticOrder, true, true, DINP>(L, g, S, E); }
;         { LAUNDER(); pg8::Gemm g{Z + ZKV, WUKV, MTOK, 1024, 256}; pg8::StaticOrder S; S.init(MTOK, 1024, 256, G, (wg + 116) % G, 1);
;           pg8::EpiBf16<0, false, true, 256, false> E{KVM, 1024, nullptr, rs2 + MTOK, nullptr, 0};
;           pg8::gemm_phase<pg8::EpiBf16<0, false, true, 256, false>, pg8::StaticOrder, true, true, DINP>(L, g, S, E); }
.LBB0_652:
	s_or_b64 exec, exec, s[2:3]
	s_waitcnt lgkmcnt(0)
	s_barrier
	s_and_b32 s101, s48, 7
	s_mov_b32 s100, 0
	s_cmp_lt_u32 s101, 3
	s_cbranch_scc1 .Lscan_late_entry
	s_mov_b32 s100, 3
	s_cmp_lt_u32 s101, 6
	s_cbranch_scc1 .LBB0_729
	s_mov_b32 s100, 1
	s_branch .LBB0_729

;     __host__ __device__ void init(int N, int K, int G_, int c_, int mode_, int rev_ = 0) { so.init(128 * BM, N, K, G_, c_, rev_); nN = N / BM; mode = mode_; }
; #define LAUNDER() int tid = tid0; asm volatile("" : "+v"(tid)); int wg = blockIdx.x; asm volatile("" : "+s"(wg)); const int lane = tid & 63, wave = __builtin_amdgcn_readfirstlane(tid >> 6), gw = wg * NWAVES + wave, NGW = G * NWAVES; (void)lane; (void)wave; (void)gw; (void)NGW
; __global__ void __launch_bounds__(NTHR, 2) fwd_kernel(Args a) {
;     ...
;         { LAUNDER(); mlstm_scan(DC, DN, SC, wg, G, tid); }
;         __syncthreads();
;         { LAUNDER(); pg8::Gemm g{Z + ZQ, WUQ, MTOK, 768, 512}; pg8::StaticOrder S; S.init(MTOK, 768, 512, G, wg, 1);
;           pg8::EpiBf16<0, false, true, 512, false> E{QM, 768, nullptr, rs2, nullptr, 0};
;           pg8::gemm_phase<pg8::EpiBf16<0, false, true, 512, false>, pg8::StaticOrder, true, true, DINP>(L, g, S, E); }
;         { LAUNDER(); pg8::Gemm g{Z + ZKV, WUKV, MTOK, 1024, 256}; pg8::StaticOrder S; S.init(MTOK, 1024, 256, G, (wg + 116) % G, 1);
;           pg8::EpiBf16<0, false, true, 256, false> E{KVM, 1024, nullptr, rs2 + MTOK, nullptr, 0};
;           pg8::gemm_phase<pg8::EpiBf16<0, false, true, 256, false>, pg8::StaticOrder, true, true, DINP>(L, g, S, E); }
.Lscan_exit:
	s_cmp_eq_u32 s100, 2
	s_cbranch_scc1 .Lbar4_go
	s_cmp_eq_u32 s100, 4
	s_cbranch_scc1 .Lukv_go

;     __host__ __device__ void init(int N, int K, int G_, int c_, int mode_, int rev_ = 0) { so.init(128 * BM, N, K, G_, c_, rev_); nN = N / BM; mode = mode_; }
; #define LAUNDER() int tid = tid0; asm volatile("" : "+v"(tid)); int wg = blockIdx.x; asm volatile("" : "+s"(wg)); const int lane = tid & 63, wave = __builtin_amdgcn_readfirstlane(tid >> 6), gw = wg * NWAVES + wave, NGW = G * NWAVES; (void)lane; (void)wave; (void)gw; (void)NGW
; __global__ void __launch_bounds__(NTHR, 2) fwd_kernel(Args a) {
;     ...
;         { LAUNDER(); pg8::Gemm g{Z + ZKV, WUKV, MTOK, 1024, 256}; pg8::StaticOrder S; S.init(MTOK, 1024, 256, G, (wg + 116) % G, 1);
;           pg8::EpiBf16<0, false, true, 256, false> E{KVM, 1024, nullptr, rs2 + MTOK, nullptr, 0};
;           pg8::gemm_phase<pg8::EpiBf16<0, false, true, 256, false>, pg8::StaticOrder, true, true, DINP>(L, g, S, E); }
.LBB0_755:
	s_cmp_lg_u32 s100, 3
	s_cbranch_scc1 .Lukv_go
	s_mov_b32 s100, 4
	s_branch .Lscan_late_entry
